# compress step: all global loads of a step issued up front (on top of previous batching and epilogue changes)
# baseline (speedup 1.0000x reference)
; __device__ __forceinline__ f32x4 MF(bf16x8 a, bf16x8 b, f32x4 c) { return __builtin_amdgcn_mfma_f32_16x16x32_bf16(a, b, c, 0, 0, 0); }
; __device__ __forceinline__ void compress_item(const Params& p, int l, int item, lptr lds) {
;     ...
;         for (int ks = 0; ks < 8; ++ks) { const bf16x8 a = ldfrag(As, (mi * 16 + fr) * 264 + ks * 32 + fq * 8);
; #pragma unroll
;             for (int i = 0; i < 4; ++i) { const bf16x8 bb = ldfrag(Bs, ((nib + i) * 16 + fr) * 264 + ks * 32 + fq * 8); acc[i] = MF(bb, a, acc[i]); } }
;         __syncthreads();
.Lmy_cmp_mfma:
	s_waitcnt lgkmcnt(0)
	s_barrier
	ds_read_b128 v[26:29], v48
	ds_read_b128 v[30:33], v49 offset:33792
	s_waitcnt lgkmcnt(0)
	v_mfma_f32_16x16x32_bf16 v[14:17], v[30:33], v[26:29], v[14:17]
	ds_read_b128 v[30:33], v50 offset:33792
	s_waitcnt lgkmcnt(0)
	v_mfma_f32_16x16x32_bf16 v[10:13], v[30:33], v[26:29], v[10:13]
	ds_read_b128 v[30:33], v51 offset:33792
	s_waitcnt lgkmcnt(0)
	v_mfma_f32_16x16x32_bf16 v[6:9], v[30:33], v[26:29], v[6:9]
	ds_read_b128 v[30:33], v52 offset:33792
	s_waitcnt lgkmcnt(0)
	v_mfma_f32_16x16x32_bf16 v[2:5], v[30:33], v[26:29], v[2:5]
	ds_read_b128 v[26:29], v48 offset:64
	ds_read_b128 v[30:33], v53 offset:33792
	s_waitcnt lgkmcnt(0)
	v_mfma_f32_16x16x32_bf16 v[14:17], v[30:33], v[26:29], v[14:17]
	ds_read_b128 v[30:33], v54 offset:33792
	s_waitcnt lgkmcnt(0)
	v_mfma_f32_16x16x32_bf16 v[10:13], v[30:33], v[26:29], v[10:13]
	ds_read_b128 v[30:33], v55 offset:33792
	s_waitcnt lgkmcnt(0)
	v_mfma_f32_16x16x32_bf16 v[6:9], v[30:33], v[26:29], v[6:9]
	ds_read_b128 v[30:33], v56 offset:33792
	s_waitcnt lgkmcnt(0)
	v_mfma_f32_16x16x32_bf16 v[2:5], v[30:33], v[26:29], v[2:5]
	ds_read_b128 v[26:29], v48 offset:128
	ds_read_b128 v[30:33], v57 offset:33792
	s_waitcnt lgkmcnt(0)
	v_mfma_f32_16x16x32_bf16 v[14:17], v[30:33], v[26:29], v[14:17]
	ds_read_b128 v[30:33], v58 offset:33792
	s_waitcnt lgkmcnt(0)
	v_mfma_f32_16x16x32_bf16 v[10:13], v[30:33], v[26:29], v[10:13]
	ds_read_b128 v[30:33], v59 offset:33792
	s_waitcnt lgkmcnt(0)
	v_mfma_f32_16x16x32_bf16 v[6:9], v[30:33], v[26:29], v[6:9]
	ds_read_b128 v[30:33], v60 offset:33792
	s_waitcnt lgkmcnt(0)
	v_mfma_f32_16x16x32_bf16 v[2:5], v[30:33], v[26:29], v[2:5]
	ds_read_b128 v[26:29], v48 offset:192
	ds_read_b128 v[30:33], v61 offset:33792
	s_waitcnt lgkmcnt(0)
	v_mfma_f32_16x16x32_bf16 v[14:17], v[30:33], v[26:29], v[14:17]
	ds_read_b128 v[30:33], v62 offset:33792
	s_waitcnt lgkmcnt(0)
	v_mfma_f32_16x16x32_bf16 v[10:13], v[30:33], v[26:29], v[10:13]
	ds_read_b128 v[30:33], v63 offset:33792
	s_waitcnt lgkmcnt(0)
	v_mfma_f32_16x16x32_bf16 v[6:9], v[30:33], v[26:29], v[6:9]
	ds_read_b128 v[30:33], v64 offset:33792
	s_waitcnt lgkmcnt(0)
	v_mfma_f32_16x16x32_bf16 v[2:5], v[30:33], v[26:29], v[2:5]
	ds_read_b128 v[26:29], v48 offset:256
	ds_read_b128 v[30:33], v65 offset:33792
	s_waitcnt lgkmcnt(0)
	v_mfma_f32_16x16x32_bf16 v[14:17], v[30:33], v[26:29], v[14:17]
	ds_read_b128 v[30:33], v66 offset:33792
	s_waitcnt lgkmcnt(0)
	v_mfma_f32_16x16x32_bf16 v[10:13], v[30:33], v[26:29], v[10:13]
	ds_read_b128 v[30:33], v67 offset:33792
	s_waitcnt lgkmcnt(0)
	v_mfma_f32_16x16x32_bf16 v[6:9], v[30:33], v[26:29], v[6:9]
	ds_read_b128 v[30:33], v68 offset:33792
	s_waitcnt lgkmcnt(0)
	v_mfma_f32_16x16x32_bf16 v[2:5], v[30:33], v[26:29], v[2:5]
	ds_read_b128 v[26:29], v48 offset:320
	ds_read_b128 v[30:33], v69 offset:33792
	s_waitcnt lgkmcnt(0)
	v_mfma_f32_16x16x32_bf16 v[14:17], v[30:33], v[26:29], v[14:17]
	ds_read_b128 v[30:33], v70 offset:33792
	s_waitcnt lgkmcnt(0)
	v_mfma_f32_16x16x32_bf16 v[10:13], v[30:33], v[26:29], v[10:13]
	ds_read_b128 v[30:33], v71 offset:33792
	s_waitcnt lgkmcnt(0)
	v_mfma_f32_16x16x32_bf16 v[6:9], v[30:33], v[26:29], v[6:9]
	ds_read_b128 v[30:33], v72 offset:33792
	s_waitcnt lgkmcnt(0)
	v_mfma_f32_16x16x32_bf16 v[2:5], v[30:33], v[26:29], v[2:5]
	ds_read_b128 v[26:29], v48 offset:384
	ds_read_b128 v[30:33], v73 offset:33792
	s_waitcnt lgkmcnt(0)
	v_mfma_f32_16x16x32_bf16 v[14:17], v[30:33], v[26:29], v[14:17]
	ds_read_b128 v[30:33], v74 offset:33792
	s_waitcnt lgkmcnt(0)
	v_mfma_f32_16x16x32_bf16 v[10:13], v[30:33], v[26:29], v[10:13]
	ds_read_b128 v[30:33], v75 offset:33792
	s_waitcnt lgkmcnt(0)
	v_mfma_f32_16x16x32_bf16 v[6:9], v[30:33], v[26:29], v[6:9]
	ds_read_b128 v[30:33], v76 offset:33792
	s_waitcnt lgkmcnt(0)
	v_mfma_f32_16x16x32_bf16 v[2:5], v[30:33], v[26:29], v[2:5]
	ds_read_b128 v[26:29], v48 offset:448
	ds_read_b128 v[30:33], v77 offset:33792
	s_waitcnt lgkmcnt(0)
	v_mfma_f32_16x16x32_bf16 v[14:17], v[30:33], v[26:29], v[14:17]
	ds_read_b128 v[30:33], v78 offset:33792
	s_waitcnt lgkmcnt(0)
	v_mfma_f32_16x16x32_bf16 v[10:13], v[30:33], v[26:29], v[10:13]
	ds_read_b128 v[30:33], v79 offset:33792
	s_waitcnt lgkmcnt(0)
	v_mfma_f32_16x16x32_bf16 v[6:9], v[30:33], v[26:29], v[6:9]
	ds_read_b128 v[30:33], v80 offset:33792
	s_waitcnt lgkmcnt(0)
	s_barrier
	v_mfma_f32_16x16x32_bf16 v[2:5], v[30:33], v[26:29], v[2:5]
	s_cbranch_scc1 .LBB0_1526
; #define LAS __attribute__((address_space(3)))
; __device__ __forceinline__ void unpack8(u32x4 v, float* f) { f[0] = lo16(v.x); f[1] = hi16(v.x); f[2] = lo16(v.y); f[3] = hi16(v.y); f[4] = lo16(v.z); f[5] = hi16(v.z); f[6] = lo16(v.w); f[7] = hi16(v.w); }
; __device__ __forceinline__ u32x4 pack8(const float* f) { u32x4 o; o.x = pk2(f[0], f[1]); o.y = pk2(f[2], f[3]); o.z = pk2(f[4], f[5]); o.w = pk2(f[6], f[7]); return o; }
; __device__ __forceinline__ void compress_item(const Params& p, int l, int item, lptr lds) {
;     ...
;         { const int r = tid >> 3, q = tid & 7, pp = q >> 1, e0 = (q & 1) * 32; const int cmp = half * 64 + r, pos = 16 * cmp + step * 4 + pp;
; #pragma unroll
;           for (int j = 0; j < 4; ++j) { float f[8];
;               if (pos < SEQ) unpack8(*(const u32x4*)(projb + (size_t)pos * PLD + col + e0 + j * 8), f); else {
; #pragma unroll
;                   for (int e = 0; e < 8; ++e) f[e] = 0.f; }
;               const float* pr = pe + (step * 4 + pp) * 64 + e0 + j * 8;
; #pragma unroll
;               for (int e = 0; e < 8; ++e) f[e] += pr[e];
;               *(LAS u32x4*)(As + ((size_t)r * 264 + pp * 64 + e0 + j * 8) * 2) = pack8(f); } }
;         { const int jrow = tid >> 2, k0 = (tid & 3) * 64;
; #pragma unroll
;           for (int j = 0; j < 8; ++j) *(LAS u32x4*)(Bs + ((size_t)jrow * 264 + k0 + j * 8) * 2) = *(const u32x4*)(w1t + (size_t)jrow * 2048 + step * 256 + k0 + j * 8); }
;         __syncthreads();
.LBB0_1518:
	s_movk_i32 s0, 0x800
	v_cmp_gt_i32_e32 vcc, s0, v47
	v_mad_i64_i32 v[26:27], s[28:29], v47, s70, v[20:21]
	v_lshl_add_u64 v[28:29], v[24:25], 0, s[26:27]
	v_mov_b32_e32 v90, 0
	v_mov_b32_e32 v91, 0
	v_mov_b32_e32 v92, 0
	v_mov_b32_e32 v93, 0
	v_mov_b32_e32 v94, 0
	v_mov_b32_e32 v95, 0
	v_mov_b32_e32 v96, 0
	v_mov_b32_e32 v97, 0
	v_mov_b32_e32 v98, 0
	v_mov_b32_e32 v99, 0
	v_mov_b32_e32 v100, 0
	v_mov_b32_e32 v101, 0
	v_mov_b32_e32 v102, 0
	v_mov_b32_e32 v103, 0
	v_mov_b32_e32 v104, 0
	v_mov_b32_e32 v105, 0
	s_and_saveexec_b64 s[28:29], vcc
	global_load_dwordx4 v[90:93], v[26:27], off
	global_load_dwordx4 v[94:97], v[26:27], off offset:16
	global_load_dwordx4 v[98:101], v[26:27], off offset:32
	global_load_dwordx4 v[102:105], v[26:27], off offset:48
	s_or_b64 exec, exec, s[28:29]
	global_load_dwordx4 v[140:143], v[28:29], off
	global_load_dwordx4 v[144:147], v[28:29], off offset:16
	global_load_dwordx4 v[148:151], v[28:29], off offset:32
	global_load_dwordx4 v[152:155], v[28:29], off offset:48
	global_load_dwordx4 v[156:159], v[28:29], off offset:64
	global_load_dwordx4 v[160:163], v[28:29], off offset:80
	global_load_dwordx4 v[164:167], v[28:29], off offset:96
	global_load_dwordx4 v[168:171], v[28:29], off offset:112
	global_load_dwordx4 v[106:109], v[22:23], off
	global_load_dwordx4 v[110:113], v[22:23], off offset:16
	global_load_dwordx4 v[114:117], v[22:23], off offset:32
	global_load_dwordx4 v[118:121], v[22:23], off offset:48
	global_load_dwordx4 v[122:125], v[22:23], off offset:64
	global_load_dwordx4 v[172:175], v[22:23], off offset:80
	global_load_dwordx4 v[176:179], v[22:23], off offset:96
	global_load_dwordx4 v[180:183], v[22:23], off offset:112
	s_add_u32 s26, s26, 0x400
	s_addc_u32 s27, s27, 0
	s_mov_b64 s[28:29], 0x200
	v_add_u32_e32 v47, 4, v47
	v_lshl_add_u64 v[22:23], v[22:23], 0, s[28:29]
	s_waitcnt vmcnt(14)
	v_lshlrev_b32_e32 v126, 16, v90
	v_and_b32_e32 v127, 0xffff0000, v90
	v_lshlrev_b32_e32 v128, 16, v91
	v_and_b32_e32 v129, 0xffff0000, v91
	v_lshlrev_b32_e32 v130, 16, v92
	v_and_b32_e32 v131, 0xffff0000, v92
	v_lshlrev_b32_e32 v132, 16, v93
	v_and_b32_e32 v133, 0xffff0000, v93
	v_pk_add_f32 v[126:127], v[126:127], v[140:141]
	v_pk_add_f32 v[128:129], v[128:129], v[142:143]
	v_pk_add_f32 v[130:131], v[130:131], v[144:145]
	v_pk_add_f32 v[132:133], v[132:133], v[146:147]
	v_cvt_pk_bf16_f32 v126, v126, v127
	v_cvt_pk_bf16_f32 v127, v128, v129
	v_cvt_pk_bf16_f32 v128, v130, v131
	v_cvt_pk_bf16_f32 v129, v132, v133
	ds_write_b128 v81, v[126:129]
	s_waitcnt vmcnt(12)
	v_lshlrev_b32_e32 v126, 16, v94
	v_and_b32_e32 v127, 0xffff0000, v94
	v_lshlrev_b32_e32 v128, 16, v95
	v_and_b32_e32 v129, 0xffff0000, v95
	v_lshlrev_b32_e32 v130, 16, v96
	v_and_b32_e32 v131, 0xffff0000, v96
	v_lshlrev_b32_e32 v132, 16, v97
	v_and_b32_e32 v133, 0xffff0000, v97
	v_pk_add_f32 v[126:127], v[126:127], v[148:149]
	v_pk_add_f32 v[128:129], v[128:129], v[150:151]
	v_pk_add_f32 v[130:131], v[130:131], v[152:153]
	v_pk_add_f32 v[132:133], v[132:133], v[154:155]
	v_cvt_pk_bf16_f32 v126, v126, v127
	v_cvt_pk_bf16_f32 v127, v128, v129
	v_cvt_pk_bf16_f32 v128, v130, v131
	v_cvt_pk_bf16_f32 v129, v132, v133
	ds_write_b128 v81, v[126:129] offset:16
	s_waitcnt vmcnt(10)
	v_lshlrev_b32_e32 v126, 16, v98
	v_and_b32_e32 v127, 0xffff0000, v98
	v_lshlrev_b32_e32 v128, 16, v99
	v_and_b32_e32 v129, 0xffff0000, v99
	v_lshlrev_b32_e32 v130, 16, v100
	v_and_b32_e32 v131, 0xffff0000, v100
	v_lshlrev_b32_e32 v132, 16, v101
	v_and_b32_e32 v133, 0xffff0000, v101
	v_pk_add_f32 v[126:127], v[126:127], v[156:157]
	v_pk_add_f32 v[128:129], v[128:129], v[158:159]
	v_pk_add_f32 v[130:131], v[130:131], v[160:161]
	v_pk_add_f32 v[132:133], v[132:133], v[162:163]
	v_cvt_pk_bf16_f32 v126, v126, v127
	v_cvt_pk_bf16_f32 v127, v128, v129
	v_cvt_pk_bf16_f32 v128, v130, v131
	v_cvt_pk_bf16_f32 v129, v132, v133
	ds_write_b128 v81, v[126:129] offset:32
	s_waitcnt vmcnt(8)
	v_lshlrev_b32_e32 v126, 16, v102
	v_and_b32_e32 v127, 0xffff0000, v102
	v_lshlrev_b32_e32 v128, 16, v103
	v_and_b32_e32 v129, 0xffff0000, v103
	v_lshlrev_b32_e32 v130, 16, v104
	v_and_b32_e32 v131, 0xffff0000, v104
	v_lshlrev_b32_e32 v132, 16, v105
	v_and_b32_e32 v133, 0xffff0000, v105
	v_pk_add_f32 v[126:127], v[126:127], v[164:165]
	v_pk_add_f32 v[128:129], v[128:129], v[166:167]
	v_pk_add_f32 v[130:131], v[130:131], v[168:169]
	v_pk_add_f32 v[132:133], v[132:133], v[170:171]
	v_cvt_pk_bf16_f32 v126, v126, v127
	v_cvt_pk_bf16_f32 v127, v128, v129
	v_cvt_pk_bf16_f32 v128, v130, v131
	v_cvt_pk_bf16_f32 v129, v132, v133
	ds_write_b128 v81, v[126:129] offset:48
	s_waitcnt vmcnt(0)
	ds_write_b128 v0, v[106:109] offset:33792
	ds_write_b128 v0, v[110:113] offset:33808
	ds_write_b128 v0, v[114:117] offset:33824
	ds_write_b128 v0, v[118:121] offset:33840
	ds_write_b128 v0, v[122:125] offset:33856
	ds_write_b128 v0, v[172:175] offset:33872
	ds_write_b128 v0, v[176:179] offset:33888
	ds_write_b128 v0, v[180:183] offset:33904
	s_cmpk_eq_i32 s26, 0x2000
	s_branch .Lmy_cmp_mfma
